# f1 + non-temporal hints on the read-once loads of the mid-norm phase and the loads/stores of the final-norm phase
# baseline (speedup 1.0000x reference)
; __device__ __forceinline__ float bflo(unsigned v) { return __uint_as_float(v << 16); }
; __device__ __forceinline__ float bfhi(unsigned v) { return __uint_as_float(v & 0xffff0000u); }
; __device__ __forceinline__ void p6_midnorm(const Args& a) {
;     ...
;     for (int m = gw; m < M; m += NGW) { u32x4* mp = (u32x4*)(MIX + (size_t)m * DM) + lane; const float* xr = a.in[I_X] + (size_t)m * DM;
;         u32x4 mv[4]; float ss = 0.f;
; #pragma unroll
;         for (int j = 0; j < 4; ++j) { mv[j] = mp[64 * j];
; #pragma unroll
;             for (int e = 0; e < 4; ++e) { const float lo = bflo(mv[j][e]), hi = bfhi(mv[j][e]); ss += lo * lo + hi * hi; } }
;         const float rs = rsqrtf(wave_sum(ss) * (1.0f / DM) + EPS);
.LBB0_1145:
	global_load_dwordx4 v[86:89], v[104:105], off nt
	global_load_dwordx4 v[82:85], v[104:105], off offset:1024 nt
	global_load_dwordx4 v[78:81], v[104:105], off offset:2048 nt
	global_load_dwordx4 v[74:77], v[104:105], off offset:3072 nt
	global_load_dwordx4 v[26:29], v[106:107], off offset:-4096 nt
	global_load_dwordx4 v[10:13], v[106:107], off offset:-4080 nt
	global_load_dwordx4 v[58:61], v[92:93], off
	global_load_dwordx4 v[42:45], v[92:93], off offset:16
	global_load_dwordx4 v[30:33], v[106:107], off offset:-2048 nt
	global_load_dwordx4 v[14:17], v[106:107], off offset:-2032 nt
	global_load_dwordx4 v[62:65], v[92:93], off offset:2048
	global_load_dwordx4 v[46:49], v[92:93], off offset:2064
	global_load_dwordx4 v[34:37], v[106:107], off nt
	global_load_dwordx4 v[18:21], v[106:107], off offset:16 nt
	global_load_dwordx4 v[66:69], v[94:95], off
	global_load_dwordx4 v[50:53], v[94:95], off offset:16
	global_load_dwordx4 v[38:41], v[106:107], off offset:2048 nt
	global_load_dwordx4 v[22:25], v[106:107], off offset:2064 nt
	global_load_dwordx4 v[70:73], v[96:97], off
	global_load_dwordx4 v[54:57], v[96:97], off offset:16
	global_load_dwordx4 v[2:5], v[98:99], off offset:16
	global_load_dwordx4 v[6:9], v[98:99], off
	v_add_co_u32_e32 v114, vcc, s12, v104
	v_add_u32_e32 v90, s4, v90
	s_nop 0
	v_addc_co_u32_e32 v115, vcc, -1, v105, vcc
	v_lshl_add_u64 v[106:107], v[106:107], 0, s[8:9]
	s_waitcnt vmcnt(0)
	v_lshlrev_b32_e32 v116, 16, v89
	v_and_b32_e32 v117, 0xffff0000, v89
	v_lshlrev_b32_e32 v118, 16, v88
	v_and_b32_e32 v119, 0xffff0000, v88
	v_lshlrev_b32_e32 v88, 16, v87
	v_and_b32_e32 v89, 0xffff0000, v87
	v_lshlrev_b32_e32 v120, 16, v86
	v_and_b32_e32 v121, 0xffff0000, v86
	v_pk_mul_f32 v[136:137], v[88:89], v[88:89]
	v_pk_mul_f32 v[138:139], v[120:121], v[120:121]
	v_pk_mul_f32 v[134:135], v[118:119], v[118:119]
	v_add_f32_e32 v136, v136, v137
	v_add_f32_e32 v137, v138, v139
	v_lshlrev_b32_e32 v86, 16, v85
	v_and_b32_e32 v87, 0xffff0000, v85
	v_lshlrev_b32_e32 v122, 16, v84
	v_and_b32_e32 v123, 0xffff0000, v84
	v_lshlrev_b32_e32 v84, 16, v83
	v_and_b32_e32 v85, 0xffff0000, v83
	v_lshlrev_b32_e32 v124, 16, v82
	v_and_b32_e32 v125, 0xffff0000, v82
	v_lshlrev_b32_e32 v82, 16, v81
	v_and_b32_e32 v83, 0xffff0000, v81
	v_lshlrev_b32_e32 v126, 16, v80
	v_and_b32_e32 v127, 0xffff0000, v80
	v_lshlrev_b32_e32 v80, 16, v79
	v_and_b32_e32 v81, 0xffff0000, v79
	v_lshlrev_b32_e32 v128, 16, v78
	v_and_b32_e32 v129, 0xffff0000, v78
	v_lshlrev_b32_e32 v78, 16, v77
	v_and_b32_e32 v79, 0xffff0000, v77
	v_lshlrev_b32_e32 v130, 16, v76
	v_and_b32_e32 v131, 0xffff0000, v76
	v_lshlrev_b32_e32 v76, 16, v75
	v_and_b32_e32 v77, 0xffff0000, v75
	v_lshlrev_b32_e32 v132, 16, v74
	v_and_b32_e32 v133, 0xffff0000, v74
	v_pk_mul_f32 v[74:75], v[116:117], v[116:117]
	v_add_f32_e32 v138, v134, v135
	v_add_f32_e32 v136, v137, v136
	v_pk_mul_f32 v[146:147], v[124:125], v[124:125]
	v_add_f32_e32 v113, v74, v75
	v_add_f32_e32 v136, v138, v136
	v_pk_mul_f32 v[144:145], v[84:85], v[84:85]
	v_add_f32_e32 v139, v146, v147
	v_add_f32_e32 v113, v113, v136
	v_pk_mul_f32 v[142:143], v[122:123], v[122:123]
	v_add_f32_e32 v144, v144, v145
	v_add_f32_e32 v113, v139, v113
	v_pk_mul_f32 v[140:141], v[86:87], v[86:87]
	v_add_f32_e32 v142, v142, v143
	v_add_f32_e32 v113, v144, v113
	v_pk_mul_f32 v[154:155], v[128:129], v[128:129]
	v_add_f32_e32 v140, v140, v141
	v_add_f32_e32 v113, v142, v113
	v_pk_mul_f32 v[152:153], v[80:81], v[80:81]
	v_add_f32_e32 v141, v154, v155
	v_add_f32_e32 v113, v140, v113
	v_pk_mul_f32 v[150:151], v[126:127], v[126:127]
	v_add_f32_e32 v143, v152, v153
	v_add_f32_e32 v113, v141, v113
	v_pk_mul_f32 v[148:149], v[82:83], v[82:83]
	v_mov_b32_e32 v162, v77
	v_mov_b32_e32 v163, v133
	v_add_f32_e32 v145, v150, v151
	v_add_f32_e32 v113, v143, v113
	v_mov_b32_e32 v160, v76
	v_mov_b32_e32 v161, v132
	v_pk_mul_f32 v[162:163], v[162:163], v[162:163]
	v_add_f32_e32 v146, v148, v149
	v_add_f32_e32 v113, v145, v113
	v_mov_b32_e32 v158, v79
	v_mov_b32_e32 v159, v131
	v_pk_fma_f32 v[134:135], v[160:161], v[160:161], v[162:163]
	v_add_f32_e32 v113, v146, v113
	v_mov_b32_e32 v156, v78
	v_mov_b32_e32 v157, v130
	v_pk_mul_f32 v[158:159], v[158:159], v[158:159]
	v_add_f32_e32 v113, v135, v113
	v_pk_fma_f32 v[74:75], v[156:157], v[156:157], v[158:159]
	v_add_f32_e32 v113, v134, v113
	v_add_f32_e32 v75, v75, v113
	v_add_f32_e32 v74, v74, v75
	ds_bpermute_b32 v75, v1, v74
	s_waitcnt lgkmcnt(0)
	v_add_f32_e32 v74, v74, v75
	ds_bpermute_b32 v75, v108, v74
	s_waitcnt lgkmcnt(0)
	v_add_f32_e32 v74, v74, v75
	ds_bpermute_b32 v75, v109, v74
	s_waitcnt lgkmcnt(0)
	v_add_f32_e32 v74, v74, v75
	ds_bpermute_b32 v75, v110, v74
	s_waitcnt lgkmcnt(0)
	v_add_f32_e32 v74, v74, v75
	ds_bpermute_b32 v75, v111, v74
	s_waitcnt lgkmcnt(0)
	v_add_f32_e32 v74, v74, v75
	ds_bpermute_b32 v75, v112, v74
	s_waitcnt lgkmcnt(0)
; __device__ __forceinline__ unsigned cvt_pk_bf16(float lo, float hi) { f32x2 v = {lo, hi}; bf16x2_t b = __builtin_convertvector(v, bf16x2_t); return __builtin_bit_cast(unsigned, b); }
; __device__ __forceinline__ float bflo(unsigned v) { return __uint_as_float(v << 16); }
; __device__ __forceinline__ float bfhi(unsigned v) { return __uint_as_float(v & 0xffff0000u); }
; __device__ __forceinline__ void p6_midnorm(const Args& a) {
;     ...
;         const float rs = rsqrtf(wave_sum(ss) * (1.0f / DM) + EPS);
;         float hv[4][8]; float s2 = 0.f;
; #pragma unroll
;         for (int j = 0; j < 4; ++j) { const int col = 512 * j + 8 * lane; const f32x4 x0 = *(const f32x4*)(xr + col), x1 = *(const f32x4*)(xr + col + 4), w0 = *(const f32x4*)(wp + col), w1 = *(const f32x4*)(wp + col + 4);
; #pragma unroll
;             for (int e = 0; e < 4; ++e) { const float lo = bflo(mv[j][e]), hi = bfhi(mv[j][e]);
;                 const float xa = (2 * e < 4) ? x0[(2 * e) & 3] : x1[(2 * e) & 3], xb = (2 * e + 1 < 4) ? x0[(2 * e + 1) & 3] : x1[(2 * e + 1) & 3];
;                 const float wa = (2 * e < 4) ? w0[(2 * e) & 3] : w1[(2 * e) & 3], wb = (2 * e + 1 < 4) ? w0[(2 * e + 1) & 3] : w1[(2 * e + 1) & 3];
;                 const float ha = xa + lo * rs * wa, hb = xb + hi * rs * wb; hv[j][2 * e] = ha; hv[j][2 * e + 1] = hb; s2 += ha * ha + hb * hb; } }
;         const float r2 = rsqrtf(wave_sum(s2) * (1.0f / DM) + EPS);
;     ...
;         for (int j = 0; j < 4; ++j) { u32x4 hq; hq.x = cvt_pk_bf16(hv[j][0], hv[j][1]); hq.y = cvt_pk_bf16(hv[j][2], hv[j][3]); hq.z = cvt_pk_bf16(hv[j][4], hv[j][5]); hq.w = cvt_pk_bf16(hv[j][6], hv[j][7]); mp[64 * j] = hq; }
	v_add_f32_e32 v74, v74, v75
	v_fmamk_f32 v74, v74, 0x3a000000, v91
	v_mul_f32_e32 v75, 0x4b800000, v74
	v_cmp_gt_f32_e32 vcc, s5, v74
	s_nop 1
	v_cndmask_b32_e32 v74, v74, v75, vcc
	v_rsq_f32_e32 v74, v74
	s_nop 0
	v_mul_f32_e32 v75, 0x45800000, v74
	v_cndmask_b32_e32 v74, v74, v75, vcc
	v_pk_mul_f32 v[120:121], v[74:75], v[120:121] op_sel_hi:[0,1]
	v_pk_mul_f32 v[88:89], v[74:75], v[88:89] op_sel_hi:[0,1]
	v_pk_mul_f32 v[118:119], v[74:75], v[118:119] op_sel_hi:[0,1]
	v_pk_mul_f32 v[116:117], v[74:75], v[116:117] op_sel_hi:[0,1]
	v_pk_mul_f32 v[124:125], v[74:75], v[124:125] op_sel_hi:[0,1]
	v_pk_mul_f32 v[86:87], v[74:75], v[86:87] op_sel_hi:[0,1]
	v_pk_fma_f32 v[26:27], v[58:59], v[120:121], v[26:27]
	v_pk_fma_f32 v[28:29], v[60:61], v[88:89], v[28:29]
	v_pk_mul_f32 v[84:85], v[74:75], v[84:85] op_sel_hi:[0,1]
	v_pk_mul_f32 v[122:123], v[74:75], v[122:123] op_sel_hi:[0,1]
	v_pk_mul_f32 v[128:129], v[74:75], v[128:129] op_sel_hi:[0,1]
	v_pk_mul_f32 v[80:81], v[74:75], v[80:81] op_sel_hi:[0,1]
	v_pk_mul_f32 v[126:127], v[74:75], v[126:127] op_sel_hi:[0,1]
	v_pk_mul_f32 v[82:83], v[74:75], v[82:83] op_sel_hi:[0,1]
	v_pk_mul_f32 v[132:133], v[74:75], v[132:133] op_sel_hi:[0,1]
	v_pk_mul_f32 v[76:77], v[74:75], v[76:77] op_sel_hi:[0,1]
	v_pk_mul_f32 v[130:131], v[74:75], v[130:131] op_sel_hi:[0,1]
	v_pk_mul_f32 v[74:75], v[74:75], v[78:79] op_sel_hi:[0,1]
	v_pk_fma_f32 v[42:43], v[42:43], v[118:119], v[10:11]
	v_pk_fma_f32 v[44:45], v[44:45], v[116:117], v[12:13]
	v_pk_fma_f32 v[30:31], v[62:63], v[124:125], v[30:31]
	v_pk_fma_f32 v[48:49], v[48:49], v[86:87], v[16:17]
	v_pk_mul_f32 v[10:11], v[26:27], v[26:27]
	v_pk_mul_f32 v[12:13], v[28:29], v[28:29]
	v_pk_fma_f32 v[46:47], v[46:47], v[122:123], v[14:15]
	v_pk_fma_f32 v[50:51], v[50:51], v[126:127], v[18:19]
	v_pk_fma_f32 v[56:57], v[56:57], v[74:75], v[24:25]
	v_pk_mul_f32 v[14:15], v[42:43], v[42:43]
	v_pk_mul_f32 v[16:17], v[44:45], v[44:45]
	v_pk_mul_f32 v[18:19], v[30:31], v[30:31]
	v_pk_mul_f32 v[24:25], v[48:49], v[48:49]
	v_add_f32_e32 v74, v12, v13
	v_add_f32_e32 v75, v10, v11
	v_add_f32_e32 v14, v14, v15
	v_add_f32_e32 v15, v16, v17
	v_add_f32_e32 v16, v18, v19
	v_add_f32_e32 v19, v24, v25
	v_add_f32_e32 v24, v75, v74
	v_pk_fma_f32 v[32:33], v[64:65], v[84:85], v[32:33]
	v_add_f32_e32 v14, v14, v24
	v_pk_fma_f32 v[52:53], v[52:53], v[82:83], v[20:21]
	v_pk_mul_f32 v[20:21], v[32:33], v[32:33]
	v_add_f32_e32 v14, v15, v14
	v_pk_fma_f32 v[54:55], v[54:55], v[130:131], v[22:23]
	v_pk_mul_f32 v[22:23], v[46:47], v[46:47]
	v_add_f32_e32 v17, v20, v21
	v_add_f32_e32 v14, v16, v14
	v_pk_fma_f32 v[34:35], v[66:67], v[128:129], v[34:35]
	v_add_f32_e32 v18, v22, v23
	v_add_f32_e32 v14, v17, v14
	v_pk_fma_f32 v[36:37], v[68:69], v[80:81], v[36:37]
	v_pk_mul_f32 v[58:59], v[34:35], v[34:35]
	v_add_f32_e32 v14, v18, v14
	v_pk_mul_f32 v[60:61], v[36:37], v[36:37]
	v_add_f32_e32 v20, v58, v59
	v_add_f32_e32 v14, v19, v14
	v_pk_fma_f32 v[38:39], v[70:71], v[132:133], v[38:39]
	v_pk_fma_f32 v[40:41], v[72:73], v[76:77], v[40:41]
	v_pk_mul_f32 v[62:63], v[50:51], v[50:51]
	v_add_f32_e32 v21, v60, v61
	v_add_f32_e32 v14, v20, v14
	v_pk_mul_f32 v[64:65], v[52:53], v[52:53]
	v_mov_b32_e32 v68, v41
	v_mov_b32_e32 v69, v39
	v_add_f32_e32 v22, v62, v63
	v_add_f32_e32 v14, v21, v14
	v_mov_b32_e32 v66, v40
	v_mov_b32_e32 v67, v38
	v_pk_mul_f32 v[68:69], v[68:69], v[68:69]
	v_add_f32_e32 v23, v64, v65
	v_add_f32_e32 v14, v22, v14
	v_mov_b32_e32 v72, v57
	v_mov_b32_e32 v73, v55
	v_pk_fma_f32 v[10:11], v[66:67], v[66:67], v[68:69]
	v_add_f32_e32 v14, v23, v14
	v_mov_b32_e32 v70, v56
	v_mov_b32_e32 v71, v54
	v_pk_mul_f32 v[72:73], v[72:73], v[72:73]
	v_add_f32_e32 v11, v11, v14
	v_pk_fma_f32 v[12:13], v[70:71], v[70:71], v[72:73]
	v_add_f32_e32 v10, v10, v11
	v_add_f32_e32 v10, v13, v10
	v_add_f32_e32 v10, v12, v10
	ds_bpermute_b32 v11, v1, v10
	v_cvt_pk_bf16_f32 v18, v34, v35
	v_cvt_pk_bf16_f32 v19, v36, v37
	v_cvt_pk_bf16_f32 v20, v50, v51
	v_cvt_pk_bf16_f32 v21, v52, v53
	s_waitcnt lgkmcnt(0)
	v_add_f32_e32 v10, v10, v11
	ds_bpermute_b32 v11, v108, v10
	v_cvt_pk_bf16_f32 v22, v38, v39
	v_cvt_pk_bf16_f32 v23, v40, v41
	v_cvt_pk_bf16_f32 v24, v54, v55
	v_cvt_pk_bf16_f32 v25, v56, v57
	s_waitcnt lgkmcnt(0)
; __device__ __forceinline__ unsigned cvt_pk_bf16(float lo, float hi) { f32x2 v = {lo, hi}; bf16x2_t b = __builtin_convertvector(v, bf16x2_t); return __builtin_bit_cast(unsigned, b); }
; __device__ __forceinline__ void p6_midnorm(const Args& a) {
;     ...
;         const float r2 = rsqrtf(wave_sum(s2) * (1.0f / DM) + EPS);
;         u32x4* up = (u32x4*)(U + (size_t)m * DM) + lane;
; #pragma unroll
;         for (int j = 0; j < 4; ++j) { const int col = 512 * j + 8 * lane; const f32x4 w0 = *(const f32x4*)(wf + col), w1 = *(const f32x4*)(wf + col + 4); u32x4 o;
;             o.x = cvt_pk_bf16(hv[j][0] * r2 * w0[0], hv[j][1] * r2 * w0[1]); o.y = cvt_pk_bf16(hv[j][2] * r2 * w0[2], hv[j][3] * r2 * w0[3]);
;             o.z = cvt_pk_bf16(hv[j][4] * r2 * w1[0], hv[j][5] * r2 * w1[1]); o.w = cvt_pk_bf16(hv[j][6] * r2 * w1[2], hv[j][7] * r2 * w1[3]); up[64 * j] = o; }
; #pragma unroll
;         for (int j = 0; j < 4; ++j) { u32x4 hq; hq.x = cvt_pk_bf16(hv[j][0], hv[j][1]); hq.y = cvt_pk_bf16(hv[j][2], hv[j][3]); hq.z = cvt_pk_bf16(hv[j][4], hv[j][5]); hq.w = cvt_pk_bf16(hv[j][6], hv[j][7]); mp[64 * j] = hq; }
;     }
	v_add_f32_e32 v10, v10, v11
	ds_bpermute_b32 v11, v109, v10
	s_waitcnt lgkmcnt(0)
	v_add_f32_e32 v10, v10, v11
	ds_bpermute_b32 v11, v110, v10
	s_waitcnt lgkmcnt(0)
	v_add_f32_e32 v10, v10, v11
	ds_bpermute_b32 v11, v111, v10
	s_waitcnt lgkmcnt(0)
	v_add_f32_e32 v10, v10, v11
	ds_bpermute_b32 v11, v112, v10
	s_waitcnt lgkmcnt(0)
	v_add_f32_e32 v10, v10, v11
	v_fmamk_f32 v10, v10, 0x3a000000, v91
	v_mul_f32_e32 v11, 0x4b800000, v10
	v_cmp_gt_f32_e32 vcc, s5, v10
	s_nop 1
	v_cndmask_b32_e32 v10, v10, v11, vcc
	v_rsq_f32_e32 v10, v10
	s_nop 0
	v_mul_f32_e32 v11, 0x45800000, v10
	v_cndmask_b32_e32 v58, v10, v11, vcc
	v_pk_mul_f32 v[10:11], v[26:27], v[58:59] op_sel_hi:[1,0]
	v_pk_mul_f32 v[12:13], v[28:29], v[58:59] op_sel_hi:[1,0]
	v_pk_mul_f32 v[14:15], v[42:43], v[58:59] op_sel_hi:[1,0]
	v_pk_mul_f32 v[16:17], v[44:45], v[58:59] op_sel_hi:[1,0]
	v_pk_mul_f32 v[6:7], v[6:7], v[10:11]
	v_pk_mul_f32 v[8:9], v[8:9], v[12:13]
	v_pk_mul_f32 v[10:11], v[2:3], v[14:15]
	v_pk_mul_f32 v[12:13], v[4:5], v[16:17]
	v_cvt_pk_bf16_f32 v2, v6, v7
	v_cvt_pk_bf16_f32 v3, v8, v9
	v_cvt_pk_bf16_f32 v4, v10, v11
	v_cvt_pk_bf16_f32 v5, v12, v13
	global_store_dwordx4 v[114:115], v[2:5], off
	global_load_dwordx4 v[2:5], v[98:99], off offset:2048
	s_nop 0
	global_load_dwordx4 v[6:9], v[98:99], off offset:2064
	v_pk_mul_f32 v[10:11], v[30:31], v[58:59] op_sel_hi:[1,0]
	v_pk_mul_f32 v[12:13], v[32:33], v[58:59] op_sel_hi:[1,0]
	v_pk_mul_f32 v[14:15], v[46:47], v[58:59] op_sel_hi:[1,0]
	v_pk_mul_f32 v[16:17], v[48:49], v[58:59] op_sel_hi:[1,0]
	v_add_co_u32_e32 v60, vcc, s13, v104
	s_waitcnt vmcnt(1)
	v_pk_mul_f32 v[2:3], v[2:3], v[10:11]
	v_pk_mul_f32 v[4:5], v[4:5], v[12:13]
	s_waitcnt vmcnt(0)
	v_pk_mul_f32 v[6:7], v[6:7], v[14:15]
	v_pk_mul_f32 v[8:9], v[8:9], v[16:17]
	v_addc_co_u32_e32 v61, vcc, -1, v105, vcc
	v_cvt_pk_bf16_f32 v2, v2, v3
	v_cvt_pk_bf16_f32 v3, v4, v5
	v_cvt_pk_bf16_f32 v4, v6, v7
	v_cvt_pk_bf16_f32 v5, v8, v9
	global_store_dwordx4 v[60:61], v[2:5], off offset:-3072
	global_load_dwordx4 v[2:5], v[100:101], off
	s_nop 0
	global_load_dwordx4 v[6:9], v[100:101], off offset:16
	v_pk_mul_f32 v[10:11], v[34:35], v[58:59] op_sel_hi:[1,0]
	v_pk_mul_f32 v[12:13], v[36:37], v[58:59] op_sel_hi:[1,0]
	v_pk_mul_f32 v[14:15], v[50:51], v[58:59] op_sel_hi:[1,0]
	v_pk_mul_f32 v[16:17], v[52:53], v[58:59] op_sel_hi:[1,0]
	v_cmp_lt_i32_e32 vcc, s14, v90
	s_or_b64 s[10:11], vcc, s[10:11]
	s_waitcnt vmcnt(1)
	v_pk_mul_f32 v[2:3], v[2:3], v[10:11]
	v_pk_mul_f32 v[4:5], v[4:5], v[12:13]
	s_waitcnt vmcnt(0)
	v_pk_mul_f32 v[6:7], v[6:7], v[14:15]
	v_pk_mul_f32 v[8:9], v[8:9], v[16:17]
	v_cvt_pk_bf16_f32 v2, v2, v3
	v_cvt_pk_bf16_f32 v3, v4, v5
	v_cvt_pk_bf16_f32 v4, v6, v7
	v_cvt_pk_bf16_f32 v5, v8, v9
	global_store_dwordx4 v[60:61], v[2:5], off offset:-2048
	global_load_dwordx4 v[2:5], v[102:103], off
	s_nop 0
	global_load_dwordx4 v[6:9], v[102:103], off offset:16
	v_cvt_pk_bf16_f32 v10, v26, v27
	v_cvt_pk_bf16_f32 v11, v28, v29
	v_cvt_pk_bf16_f32 v14, v30, v31
	v_cvt_pk_bf16_f32 v15, v32, v33
	v_pk_mul_f32 v[26:27], v[38:39], v[58:59] op_sel_hi:[1,0]
	v_pk_mul_f32 v[28:29], v[40:41], v[58:59] op_sel_hi:[1,0]
	v_pk_mul_f32 v[30:31], v[54:55], v[58:59] op_sel_hi:[1,0]
	v_pk_mul_f32 v[32:33], v[56:57], v[58:59] op_sel_hi:[1,0]
	v_cvt_pk_bf16_f32 v12, v42, v43
	v_cvt_pk_bf16_f32 v13, v44, v45
	v_cvt_pk_bf16_f32 v16, v46, v47
	v_cvt_pk_bf16_f32 v17, v48, v49
	global_store_dwordx4 v[104:105], v[10:13], off
	global_store_dwordx4 v[104:105], v[14:17], off offset:1024
	global_store_dwordx4 v[104:105], v[18:21], off offset:2048
	global_store_dwordx4 v[104:105], v[22:25], off offset:3072
	v_lshl_add_u64 v[104:105], v[104:105], 0, s[6:7]
	s_waitcnt vmcnt(5)
	v_pk_mul_f32 v[2:3], v[2:3], v[26:27]
	v_pk_mul_f32 v[4:5], v[4:5], v[28:29]
	s_waitcnt vmcnt(4)
	v_pk_mul_f32 v[6:7], v[6:7], v[30:31]
	v_pk_mul_f32 v[8:9], v[8:9], v[32:33]
	v_cvt_pk_bf16_f32 v2, v2, v3
	v_cvt_pk_bf16_f32 v3, v4, v5
	v_cvt_pk_bf16_f32 v4, v6, v7
	v_cvt_pk_bf16_f32 v5, v8, v9
	global_store_dwordx4 v[60:61], v[2:5], off offset:-1024
	s_andn2_b64 exec, exec, s[10:11]
	s_cbranch_execnz .LBB0_1145

; __device__ __forceinline__ void p9_final(const Args& a) {
;     ...
;     for (int m0 = gw * P9R; m0 < M; m0 += NGW * P9R) {
;         u32x2 hv[P9R][8], fv[P9R][8];
; #pragma unroll
;         for (int r = 0; r < P9R; ++r) { const u32x2* hp = (const u32x2*)(H1 + (size_t)(m0 + r) * DM) + lane; const u32x2* fp = (const u32x2*)(FFN + (size_t)(m0 + r) * DM) + lane;
; #pragma unroll
;             for (int j = 0; j < 8; ++j) { hv[r][j] = hp[64 * j]; fv[r][j] = fp[64 * j]; } }
.LBB0_1380:
	v_add_co_u32_e64 v40, s[0:1], s11, v18
	v_add_co_u32_e32 v52, vcc, 0xffffd000, v18
	s_nop 0
	v_addc_co_u32_e64 v41, s[0:1], -1, v19, s[0:1]
	v_add_co_u32_e64 v42, s[0:1], s12, v18
	v_addc_co_u32_e32 v53, vcc, -1, v19, vcc
	s_nop 0
	v_addc_co_u32_e64 v43, s[0:1], -1, v19, s[0:1]
	v_add_co_u32_e64 v54, s[0:1], s14, v18
	global_load_dwordx2 v[38:39], v[18:19], off offset:-4096 nt
	s_nop 0
	v_addc_co_u32_e64 v55, s[0:1], -1, v19, s[0:1]
	v_add_co_u32_e64 v56, s[0:1], s13, v18
	global_load_dwordx2 v[36:37], v[18:19], off offset:-3584 nt
	global_load_dwordx2 v[34:35], v[18:19], off offset:-3072 nt
	global_load_dwordx2 v[32:33], v[18:19], off offset:-2560 nt
	global_load_dwordx2 v[30:31], v[18:19], off offset:-2048 nt
	global_load_dwordx2 v[28:29], v[18:19], off offset:-1536 nt
	global_load_dwordx2 v[26:27], v[18:19], off offset:-1024 nt
	global_load_dwordx2 v[24:25], v[18:19], off offset:-512 nt
	global_load_dwordx2 v[22:23], v[18:19], off nt
	global_load_dwordx4 v[0:3], v[6:7], off
	v_addc_co_u32_e64 v57, s[0:1], -1, v19, s[0:1]
	v_add_co_u32_e64 v58, s[0:1], s15, v18
	v_add_co_u32_e32 v98, vcc, 0xf7ffd000, v18
	s_nop 0
	v_addc_co_u32_e64 v59, s[0:1], -1, v19, s[0:1]
	global_load_dwordx2 v[110:111], v[40:41], off offset:-3584 nt
	global_load_dwordx2 v[116:117], v[40:41], off offset:-3072 nt
	global_load_dwordx2 v[112:113], v[40:41], off offset:-2560 nt
	global_load_dwordx2 v[114:115], v[40:41], off offset:-2048 nt
	global_load_dwordx2 v[100:101], v[42:43], off offset:-3584 nt
	global_load_dwordx2 v[106:107], v[42:43], off offset:-3072 nt
	global_load_dwordx2 v[108:109], v[42:43], off offset:-2560 nt
	global_load_dwordx2 v[120:121], v[42:43], off offset:-2048 nt
	global_load_dwordx2 v[102:103], v[40:41], off offset:-1536 nt
	global_load_dwordx2 v[96:97], v[40:41], off offset:-1024 nt
	global_load_dwordx2 v[94:95], v[40:41], off offset:-512 nt
	global_load_dwordx2 v[92:93], v[40:41], off nt
	global_load_dwordx2 v[152:153], v[42:43], off offset:-1536 nt
	global_load_dwordx2 v[154:155], v[42:43], off offset:-1024 nt
	global_load_dwordx2 v[156:157], v[42:43], off offset:-512 nt
	global_load_dwordx2 v[88:89], v[56:57], off offset:-3584 nt
	global_load_dwordx2 v[50:51], v[56:57], off offset:-3072 nt
	global_load_dwordx2 v[48:49], v[56:57], off offset:-2560 nt
	global_load_dwordx2 v[46:47], v[56:57], off offset:-2048 nt
	global_load_dwordx2 v[44:45], v[56:57], off offset:-1536 nt
	global_load_dwordx2 v[90:91], v[54:55], off offset:-3072 nt
	global_load_dwordx2 v[86:87], v[54:55], off offset:-2560 nt
	global_load_dwordx2 v[84:85], v[54:55], off offset:-2048 nt
	global_load_dwordx2 v[82:83], v[54:55], off offset:-1536 nt
	global_load_dwordx2 v[80:81], v[54:55], off offset:-1024 nt
	global_load_dwordx2 v[78:79], v[54:55], off offset:-512 nt
	global_load_dwordx2 v[76:77], v[54:55], off nt
	global_load_dwordx2 v[42:43], v[56:57], off offset:-1024 nt
	global_load_dwordx2 v[40:41], v[56:57], off offset:-512 nt
	global_load_dwordx2 v[74:75], v[58:59], off offset:-3584 nt
	global_load_dwordx2 v[72:73], v[58:59], off offset:-3072 nt
	global_load_dwordx2 v[70:71], v[58:59], off offset:-2560 nt
	global_load_dwordx2 v[68:69], v[58:59], off offset:-2048 nt
	global_load_dwordx2 v[66:67], v[58:59], off offset:-1536 nt
	global_load_dwordx2 v[62:63], v[58:59], off offset:-1024 nt
	global_load_dwordx2 v[158:159], v[54:55], off offset:-4096 nt
	global_load_dwordx2 v[104:105], v[54:55], off offset:-3584 nt
	global_load_dwordx2 v[64:65], v[58:59], off offset:-512 nt
	global_load_dwordx2 v[60:61], v[58:59], off nt
	global_load_dwordx2 v[160:161], v[52:53], off offset:-3584 nt
	v_addc_co_u32_e32 v99, vcc, -1, v19, vcc
	global_load_dwordx2 v[162:163], v[52:53], off offset:-3072 nt
	global_load_dwordx2 v[164:165], v[52:53], off offset:-2560 nt
	global_load_dwordx2 v[144:145], v[52:53], off offset:-2048 nt
	global_load_dwordx2 v[142:143], v[52:53], off offset:-1536 nt
	global_load_dwordx2 v[140:141], v[52:53], off offset:-1024 nt
	global_load_dwordx2 v[136:137], v[52:53], off offset:-512 nt
	global_load_dwordx2 v[134:135], v[52:53], off nt
	global_load_dwordx2 v[166:167], v[98:99], off offset:-3584 nt
	global_load_dwordx2 v[168:169], v[98:99], off offset:-3072 nt
	global_load_dwordx2 v[170:171], v[98:99], off offset:-2560 nt
	global_load_dwordx2 v[172:173], v[98:99], off offset:-2048 nt
	global_load_dwordx2 v[174:175], v[98:99], off offset:-1536 nt
	global_load_dwordx2 v[176:177], v[98:99], off offset:-1024 nt
	global_load_dwordx2 v[178:179], v[98:99], off offset:-512 nt
	global_load_dwordx2 v[180:181], v[98:99], off nt
	s_waitcnt vmcnt(0)
; __device__ __forceinline__ float bflo(unsigned v) { return __uint_as_float(v << 16); }
; __device__ __forceinline__ float bfhi(unsigned v) { return __uint_as_float(v & 0xffff0000u); }
; __device__ __forceinline__ void p9_final(const Args& a) {
;     ...
;         for (int r = 0; r < P9R; ++r) { float s2 = 0.f;
; #pragma unroll
;             for (int j = 0; j < 8; ++j) { const float b0 = bflo(fv[r][j].x), b1 = bfhi(fv[r][j].x), b2 = bflo(fv[r][j].y), b3 = bfhi(fv[r][j].y); s2 += (b0 * b0 + b1 * b1) + (b2 * b2 + b3 * b3); }
;             r2[r] = rsqrtf(wave_sum(s2) * (1.0f / DM) + EPS); }
	v_add_co_u32_e64 v138, s[0:1], s17, v16
	v_add_u32_e32 v4, s2, v4
	s_nop 0
	v_addc_co_u32_e64 v139, s[0:1], -1, v17, s[0:1]
	v_lshl_add_u64 v[18:19], v[18:19], 0, s[6:7]
	v_and_b32_e32 v131, 0xffff0000, v100
	v_lshlrev_b32_e32 v132, 16, v101
	v_and_b32_e32 v133, 0xffff0000, v101
	v_and_b32_e32 v129, 0xffff0000, v106
	v_and_b32_e32 v127, 0xffff0000, v107
	v_and_b32_e32 v125, 0xffff0000, v108
	v_and_b32_e32 v123, 0xffff0000, v109
	v_lshlrev_b32_e32 v118, 16, v120
	v_and_b32_e32 v119, 0xffff0000, v120
	v_lshlrev_b32_e32 v120, 16, v121
	v_and_b32_e32 v121, 0xffff0000, v121
	v_and_b32_e32 v99, 0xffff0000, v154
	v_and_b32_e32 v101, 0xffff0000, v155
	v_lshlrev_b32_e32 v130, 16, v100
	v_lshlrev_b32_e32 v128, 16, v106
	v_lshlrev_b32_e32 v126, 16, v107
	v_lshlrev_b32_e32 v124, 16, v108
	v_lshlrev_b32_e32 v122, 16, v109
	v_lshlrev_b32_e32 v108, 16, v153
	v_and_b32_e32 v109, 0xffff0000, v153
	v_lshlrev_b32_e32 v98, 16, v154
	v_lshlrev_b32_e32 v100, 16, v155
	v_and_b32_e32 v57, 0xffff0000, v156
	v_and_b32_e32 v59, 0xffff0000, v157
	v_mov_b32_e32 v182, v133
	v_mov_b32_e32 v183, v127
	v_mov_b32_e32 v186, v125
	v_mov_b32_e32 v187, v123
	v_mul_f32_e32 v188, v119, v119
	v_mul_f32_e32 v190, v121, v121
	v_mov_b32_e32 v198, v99
	v_mov_b32_e32 v199, v101
	v_lshlrev_b32_e32 v106, 16, v152
	v_and_b32_e32 v107, 0xffff0000, v152
	v_lshlrev_b32_e32 v52, 16, v158
	v_and_b32_e32 v53, 0xffff0000, v158
	v_lshlrev_b32_e32 v54, 16, v159
	v_and_b32_e32 v55, 0xffff0000, v159
	v_mov_b32_e32 v158, v131
	v_mov_b32_e32 v159, v129
	v_lshlrev_b32_e32 v208, 16, v166
	v_and_b32_e32 v209, 0xffff0000, v166
	v_lshlrev_b32_e32 v166, 16, v167
	v_and_b32_e32 v167, 0xffff0000, v167
	v_lshlrev_b32_e32 v210, 16, v168
	v_and_b32_e32 v211, 0xffff0000, v168
	v_lshlrev_b32_e32 v168, 16, v169
	v_and_b32_e32 v169, 0xffff0000, v169
	v_lshlrev_b32_e32 v56, 16, v156
	v_lshlrev_b32_e32 v58, 16, v157
	v_lshlrev_b32_e32 v152, 16, v160
	v_and_b32_e32 v153, 0xffff0000, v160
	v_lshlrev_b32_e32 v154, 16, v161
	v_and_b32_e32 v155, 0xffff0000, v161
	v_mov_b32_e32 v156, v130
	v_mov_b32_e32 v157, v128
	v_mov_b32_e32 v160, v132
	v_mov_b32_e32 v161, v126
	v_mov_b32_e32 v184, v124
	v_mov_b32_e32 v185, v122
	v_pk_mul_f32 v[194:195], v[108:109], v[108:109]
	v_mov_b32_e32 v196, v98
	v_mov_b32_e32 v197, v100
	v_mul_f32_e32 v200, v57, v57
	v_mul_f32_e32 v202, v59, v59
	v_lshlrev_b32_e32 v212, 16, v170
	v_and_b32_e32 v213, 0xffff0000, v170
	v_lshlrev_b32_e32 v170, 16, v171
	v_and_b32_e32 v171, 0xffff0000, v171
	v_and_b32_e32 v215, 0xffff0000, v172
	v_lshlrev_b32_e32 v220, 16, v178
	v_and_b32_e32 v221, 0xffff0000, v178
	v_lshlrev_b32_e32 v178, 16, v179
	v_and_b32_e32 v179, 0xffff0000, v179
	v_pk_mul_f32 v[158:159], v[158:159], v[158:159]
	v_pk_mul_f32 v[182:183], v[182:183], v[182:183]
	v_pk_mul_f32 v[186:187], v[186:187], v[186:187]
	v_pk_fma_f32 v[188:189], v[118:119], v[118:119], v[188:189] op_sel_hi:[1,1,0]
	v_pk_fma_f32 v[190:191], v[120:121], v[120:121], v[190:191] op_sel_hi:[1,1,0]
	v_pk_mul_f32 v[198:199], v[198:199], v[198:199]
	v_mov_b32_e32 v226, v209
	v_mov_b32_e32 v227, v211
	v_mov_b32_e32 v230, v167
	v_mov_b32_e32 v231, v169
	v_pk_mul_f32 v[206:207], v[54:55], v[54:55]
	v_lshlrev_b32_e32 v214, 16, v172
	v_lshlrev_b32_e32 v222, 16, v180
	v_and_b32_e32 v223, 0xffff0000, v180
	v_lshlrev_b32_e32 v180, 16, v181
	v_and_b32_e32 v181, 0xffff0000, v181
	v_pk_fma_f32 v[200:201], v[56:57], v[56:57], v[200:201] op_sel_hi:[1,1,0]
	v_pk_fma_f32 v[202:203], v[58:59], v[58:59], v[202:203] op_sel_hi:[1,1,0]
	v_mov_b32_e32 v224, v208
	v_mov_b32_e32 v225, v210
	v_mov_b32_e32 v228, v166
	v_mov_b32_e32 v229, v168
	v_mov_b32_e32 v234, v213
	v_mov_b32_e32 v235, v171
	v_mul_f32_e32 v236, v215, v215
	v_mul_f32_e32 v248, v221, v221
	v_mul_f32_e32 v250, v179, v179
	v_pk_fma_f32 v[156:157], v[156:157], v[156:157], v[158:159]
	v_pk_fma_f32 v[160:161], v[160:161], v[160:161], v[182:183]
	v_pk_fma_f32 v[184:185], v[184:185], v[184:185], v[186:187]
	v_mov_b32_e32 v189, v194
	v_mov_b32_e32 v191, v195
	v_pk_fma_f32 v[186:187], v[196:197], v[196:197], v[198:199]
	v_pk_mul_f32 v[194:195], v[226:227], v[226:227]
	v_pk_mul_f32 v[196:197], v[230:231], v[230:231]
	v_lshlrev_b32_e32 v172, 16, v173
	v_and_b32_e32 v173, 0xffff0000, v173
	v_mov_b32_e32 v232, v212
	v_mov_b32_e32 v233, v170
	v_pk_mul_f32 v[182:183], v[180:181], v[180:181]
	v_mov_b32_e32 v201, v206
	v_mov_b32_e32 v203, v207
	v_pk_mul_f32 v[198:199], v[234:235], v[234:235]
	v_pk_fma_f32 v[206:207], v[214:215], v[214:215], v[236:237] op_sel_hi:[1,1,0]
	v_pk_fma_f32 v[234:235], v[220:221], v[220:221], v[248:249] op_sel_hi:[1,1,0]
	v_pk_fma_f32 v[236:237], v[178:179], v[178:179], v[250:251] op_sel_hi:[1,1,0]
	v_pk_add_f32 v[156:157], v[156:157], v[160:161]
	v_pk_add_f32 v[160:161], v[184:185], v[184:185] op_sel:[0,1] op_sel_hi:[1,0]
	v_pk_add_f32 v[184:185], v[188:189], v[190:191]
	v_pk_fma_f32 v[190:191], v[224:225], v[224:225], v[194:195]
	v_pk_fma_f32 v[194:195], v[228:229], v[228:229], v[196:197]
	v_lshlrev_b32_e32 v216, 16, v174
	v_and_b32_e32 v217, 0xffff0000, v174
	v_lshlrev_b32_e32 v174, 16, v175
	v_and_b32_e32 v175, 0xffff0000, v175
	v_mul_f32_e32 v238, v173, v173
	v_pk_fma_f32 v[196:197], v[232:233], v[232:233], v[198:199]
	v_mov_b32_e32 v235, v182
	v_mov_b32_e32 v237, v183
	v_pk_add_f32 v[182:183], v[190:191], v[194:195]
	v_pk_mul_f32 v[192:193], v[106:107], v[106:107]
	v_lshlrev_b32_e32 v218, 16, v176
	v_and_b32_e32 v219, 0xffff0000, v176
	v_lshlrev_b32_e32 v176, 16, v177
	v_and_b32_e32 v177, 0xffff0000, v177
	v_pk_mul_f32 v[240:241], v[216:217], v[216:217]
	v_pk_mul_f32 v[242:243], v[174:175], v[174:175]
	v_pk_fma_f32 v[226:227], v[172:173], v[172:173], v[238:239] op_sel_hi:[1,1,0]
; __device__ __forceinline__ float bflo(unsigned v) { return __uint_as_float(v << 16); }
; __device__ __forceinline__ float bfhi(unsigned v) { return __uint_as_float(v & 0xffff0000u); }
; __device__ __forceinline__ void p9_final(const Args& a) {
;     ...
;         for (int r = 0; r < P9R; ++r) { float s2 = 0.f;
; #pragma unroll
;             for (int j = 0; j < 8; ++j) { const float b0 = bflo(fv[r][j].x), b1 = bfhi(fv[r][j].x), b2 = bflo(fv[r][j].y), b3 = bfhi(fv[r][j].y); s2 += (b0 * b0 + b1 * b1) + (b2 * b2 + b3 * b3); }
;             r2[r] = rsqrtf(wave_sum(s2) * (1.0f / DM) + EPS); }
; #pragma unroll
;         for (int r = 0; r < P9R; ++r) { f32x4* orow = (f32x4*)(a.out + (size_t)(m0 + r) * DM) + lane;
; #pragma unroll
;             for (int j = 0; j < 8; ++j) { const f32x4 w2 = wf[64 * j]; f32x4 o;
;                 o[0] = bflo(hv[r][j].x) + bflo(fv[r][j].x) * r2[r] * w2[0]; o[1] = bfhi(hv[r][j].x) + bfhi(fv[r][j].x) * r2[r] * w2[1];
;                 o[2] = bflo(hv[r][j].y) + bflo(fv[r][j].y) * r2[r] * w2[2]; o[3] = bfhi(hv[r][j].y) + bfhi(fv[r][j].y) * r2[r] * w2[3];
;                 orow[64 * j] = o; } }
	v_pk_add_f32 v[156:157], v[156:157], v[156:157] op_sel:[0,1] op_sel_hi:[1,0]
	v_pk_add_f32 v[190:191], v[196:197], v[196:197] op_sel:[0,1] op_sel_hi:[1,0]
	v_pk_add_f32 v[182:183], v[182:183], v[182:183] op_sel:[0,1] op_sel_hi:[1,0]
	v_mov_b32_e32 v246, v219
	v_mov_b32_e32 v247, v177
	v_mov_b32_e32 v207, v242
	v_mov_b32_e32 v227, v243
	v_mov_b32_e32 v161, v193
	v_mov_b32_e32 v157, v192
	v_mov_b32_e32 v191, v241
	v_mov_b32_e32 v183, v240
	v_mov_b32_e32 v244, v218
	v_mov_b32_e32 v245, v176
	v_pk_mul_f32 v[230:231], v[246:247], v[246:247]
	v_pk_add_f32 v[194:195], v[206:207], v[226:227]
	v_pk_add_f32 v[156:157], v[156:157], v[160:161]
	v_pk_add_f32 v[160:161], v[182:183], v[190:191]
	v_pk_fma_f32 v[198:199], v[244:245], v[244:245], v[230:231]
	v_pk_add_f32 v[156:157], v[156:157], v[184:185]
	v_pk_add_f32 v[160:161], v[160:161], v[194:195]
	v_pk_mul_f32 v[204:205], v[52:53], v[52:53]
	v_pk_mul_f32 v[158:159], v[222:223], v[222:223]
	v_pk_add_f32 v[186:187], v[186:187], v[186:187] op_sel:[0,1] op_sel_hi:[1,0]
	v_pk_add_f32 v[196:197], v[198:199], v[198:199] op_sel:[0,1] op_sel_hi:[1,0]
	v_pk_add_f32 v[156:157], v[156:157], v[156:157] op_sel:[0,1] op_sel_hi:[1,0]
	v_pk_add_f32 v[160:161], v[160:161], v[160:161] op_sel:[0,1] op_sel_hi:[1,0]
	v_mov_b32_e32 v187, v205
	v_mov_b32_e32 v197, v159
	v_mov_b32_e32 v157, v204
	v_mov_b32_e32 v161, v158
	v_pk_add_f32 v[188:189], v[200:201], v[202:203]
	v_pk_add_f32 v[198:199], v[234:235], v[236:237]
	v_pk_add_f32 v[156:157], v[156:157], v[186:187]
	v_pk_add_f32 v[158:159], v[160:161], v[196:197]
	v_pk_add_f32 v[156:157], v[156:157], v[188:189]
	v_pk_add_f32 v[158:159], v[158:159], v[198:199]
	v_mov_b32_e32 v160, v156
	v_mov_b32_e32 v161, v158
	v_mov_b32_e32 v158, v157
	v_pk_add_f32 v[156:157], v[160:161], v[158:159]
	ds_bpermute_b32 v159, v146, v157
	ds_bpermute_b32 v158, v146, v156
	s_waitcnt lgkmcnt(0)
	v_pk_add_f32 v[156:157], v[156:157], v[158:159]
	ds_bpermute_b32 v159, v147, v157
	ds_bpermute_b32 v158, v147, v156
	s_waitcnt lgkmcnt(0)
	v_pk_add_f32 v[156:157], v[156:157], v[158:159]
	ds_bpermute_b32 v159, v148, v157
	ds_bpermute_b32 v158, v148, v156
	s_waitcnt lgkmcnt(0)
	v_pk_add_f32 v[156:157], v[156:157], v[158:159]
	ds_bpermute_b32 v159, v149, v157
	ds_bpermute_b32 v158, v149, v156
	s_waitcnt lgkmcnt(0)
	v_pk_add_f32 v[156:157], v[156:157], v[158:159]
	ds_bpermute_b32 v159, v150, v157
	ds_bpermute_b32 v158, v150, v156
	s_waitcnt lgkmcnt(0)
	v_pk_add_f32 v[156:157], v[156:157], v[158:159]
	ds_bpermute_b32 v159, v151, v157
	ds_bpermute_b32 v158, v151, v156
	s_waitcnt lgkmcnt(0)
	v_pk_add_f32 v[156:157], v[156:157], v[158:159]
	s_nop 0
	v_pk_fma_f32 v[156:157], v[156:157], s[10:11], v[20:21] op_sel_hi:[1,0,0]
	s_nop 0
	v_mul_f32_e32 v5, 0x4b800000, v157
	v_cmp_gt_f32_e32 vcc, s16, v157
	s_nop 1
	v_cndmask_b32_e32 v5, v157, v5, vcc
	v_rsq_f32_e32 v5, v5
	s_nop 0
	v_mul_f32_e32 v157, 0x45800000, v5
	v_cndmask_b32_e32 v158, v5, v157, vcc
	v_pk_mul_f32 v[160:161], v[158:159], v[208:209] op_sel_hi:[0,1]
	v_pk_mul_f32 v[166:167], v[158:159], v[166:167] op_sel_hi:[0,1]
	v_pk_fma_f32 v[0:1], v[160:161], v[0:1], v[152:153]
	v_pk_fma_f32 v[2:3], v[166:167], v[2:3], v[154:155]
	global_store_dwordx4 v[138:139], v[0:3], off offset:-3072 nt
	global_load_dwordx4 v[0:3], v[6:7], off offset:1024
	v_lshlrev_b32_e32 v152, 16, v162
	v_and_b32_e32 v153, 0xffff0000, v162
	v_lshlrev_b32_e32 v154, 16, v163
	v_and_b32_e32 v155, 0xffff0000, v163
	v_pk_mul_f32 v[160:161], v[158:159], v[210:211] op_sel_hi:[0,1]
	v_pk_mul_f32 v[162:163], v[158:159], v[168:169] op_sel_hi:[0,1]
	v_mul_f32_e32 v5, 0x4b800000, v156
	s_waitcnt vmcnt(0)
	v_pk_fma_f32 v[0:1], v[160:161], v[0:1], v[152:153]
	v_pk_fma_f32 v[2:3], v[162:163], v[2:3], v[154:155]
	global_store_dwordx4 v[138:139], v[0:3], off offset:-2048 nt
	global_load_dwordx4 v[0:3], v[6:7], off offset:2048
	v_lshlrev_b32_e32 v152, 16, v164
	v_and_b32_e32 v153, 0xffff0000, v164
	v_lshlrev_b32_e32 v154, 16, v165
	v_and_b32_e32 v155, 0xffff0000, v165
	v_pk_mul_f32 v[160:161], v[158:159], v[212:213] op_sel_hi:[0,1]
	v_pk_mul_f32 v[162:163], v[158:159], v[170:171] op_sel_hi:[0,1]
	s_waitcnt vmcnt(0)
	v_pk_fma_f32 v[0:1], v[160:161], v[0:1], v[152:153]
	v_pk_fma_f32 v[2:3], v[162:163], v[2:3], v[154:155]
	global_store_dwordx4 v[138:139], v[0:3], off offset:-1024 nt
	global_load_dwordx4 v[0:3], v[6:7], off offset:3072
	v_add_co_u32_e32 v138, vcc, s18, v16
	v_lshlrev_b32_e32 v152, 16, v144
	v_and_b32_e32 v153, 0xffff0000, v144
	v_lshlrev_b32_e32 v144, 16, v145
	v_and_b32_e32 v145, 0xffff0000, v145
	v_pk_mul_f32 v[154:155], v[158:159], v[214:215] op_sel_hi:[0,1]
	v_pk_mul_f32 v[160:161], v[158:159], v[172:173] op_sel_hi:[0,1]
	v_addc_co_u32_e32 v139, vcc, -1, v17, vcc
	s_waitcnt vmcnt(0)
	v_pk_fma_f32 v[0:1], v[154:155], v[0:1], v[152:153]
	v_pk_fma_f32 v[2:3], v[160:161], v[2:3], v[144:145]
	global_store_dwordx4 v[138:139], v[0:3], off offset:-4096 nt
	global_load_dwordx4 v[0:3], v[8:9], off
	v_lshlrev_b32_e32 v144, 16, v142
	v_and_b32_e32 v145, 0xffff0000, v142
	v_lshlrev_b32_e32 v142, 16, v143
	v_and_b32_e32 v143, 0xffff0000, v143
	v_pk_mul_f32 v[152:153], v[158:159], v[216:217] op_sel_hi:[0,1]
	v_pk_mul_f32 v[154:155], v[158:159], v[174:175] op_sel_hi:[0,1]
	s_waitcnt vmcnt(0)
	v_pk_fma_f32 v[0:1], v[152:153], v[0:1], v[144:145]
	v_pk_fma_f32 v[2:3], v[154:155], v[2:3], v[142:143]
	global_store_dwordx4 v[138:139], v[0:3], off offset:-3072 nt
	global_load_dwordx4 v[0:3], v[10:11], off
	v_lshlrev_b32_e32 v142, 16, v140
	v_and_b32_e32 v143, 0xffff0000, v140
	v_lshlrev_b32_e32 v140, 16, v141
	v_and_b32_e32 v141, 0xffff0000, v141
	v_pk_mul_f32 v[144:145], v[158:159], v[218:219] op_sel_hi:[0,1]
	v_pk_mul_f32 v[152:153], v[158:159], v[176:177] op_sel_hi:[0,1]
	v_lshlrev_b32_e32 v154, 16, v87
	v_and_b32_e32 v155, 0xffff0000, v87
	v_and_b32_e32 v87, 0xffff0000, v72
	v_mov_b32_e32 v183, v87
	v_mov_b32_e32 v157, v154
	s_waitcnt vmcnt(0)
; __device__ __forceinline__ float bflo(unsigned v) { return __uint_as_float(v << 16); }
; __device__ __forceinline__ float bfhi(unsigned v) { return __uint_as_float(v & 0xffff0000u); }
; __device__ __forceinline__ void p9_final(const Args& a) {
;     ...
;             r2[r] = rsqrtf(wave_sum(s2) * (1.0f / DM) + EPS); }
; #pragma unroll
;         for (int r = 0; r < P9R; ++r) { f32x4* orow = (f32x4*)(a.out + (size_t)(m0 + r) * DM) + lane;
; #pragma unroll
;             for (int j = 0; j < 8; ++j) { const f32x4 w2 = wf[64 * j]; f32x4 o;
;                 o[0] = bflo(hv[r][j].x) + bflo(fv[r][j].x) * r2[r] * w2[0]; o[1] = bfhi(hv[r][j].x) + bfhi(fv[r][j].x) * r2[r] * w2[1];
;                 o[2] = bflo(hv[r][j].y) + bflo(fv[r][j].y) * r2[r] * w2[2]; o[3] = bfhi(hv[r][j].y) + bfhi(fv[r][j].y) * r2[r] * w2[3];
;                 orow[64 * j] = o; } }
	v_pk_fma_f32 v[0:1], v[144:145], v[0:1], v[142:143]
	v_pk_fma_f32 v[2:3], v[152:153], v[2:3], v[140:141]
	global_store_dwordx4 v[138:139], v[0:3], off offset:-2048 nt
	global_load_dwordx4 v[0:3], v[12:13], off
	v_lshlrev_b32_e32 v140, 16, v136
	v_and_b32_e32 v141, 0xffff0000, v136
	v_lshlrev_b32_e32 v136, 16, v137
	v_and_b32_e32 v137, 0xffff0000, v137
	v_pk_mul_f32 v[142:143], v[158:159], v[220:221] op_sel_hi:[0,1]
	v_pk_mul_f32 v[144:145], v[158:159], v[178:179] op_sel_hi:[0,1]
	v_lshlrev_b32_e32 v152, 16, v86
	v_and_b32_e32 v153, 0xffff0000, v86
	v_lshlrev_b32_e32 v86, 16, v72
	v_lshlrev_b32_e32 v72, 16, v67
	s_waitcnt vmcnt(0)
	v_pk_fma_f32 v[0:1], v[142:143], v[0:1], v[140:141]
	v_pk_fma_f32 v[2:3], v[144:145], v[2:3], v[136:137]
	global_store_dwordx4 v[138:139], v[0:3], off offset:-1024 nt
	global_load_dwordx4 v[0:3], v[14:15], off
	v_lshlrev_b32_e32 v136, 16, v134
	v_and_b32_e32 v137, 0xffff0000, v134
	v_lshlrev_b32_e32 v134, 16, v135
	v_and_b32_e32 v135, 0xffff0000, v135
	v_pk_mul_f32 v[140:141], v[158:159], v[222:223] op_sel_hi:[0,1]
	v_pk_mul_f32 v[142:143], v[158:159], v[180:181] op_sel_hi:[0,1]
	v_lshlrev_b32_e32 v144, 16, v91
	v_and_b32_e32 v145, 0xffff0000, v91
	v_and_b32_e32 v91, 0xffff0000, v75
	v_mov_b32_e32 v158, v153
	v_mov_b32_e32 v159, v155
	v_mov_b32_e32 v186, v91
	v_mov_b32_e32 v181, v86
	s_waitcnt vmcnt(0)
	v_pk_fma_f32 v[0:1], v[140:141], v[0:1], v[136:137]
	v_pk_fma_f32 v[2:3], v[142:143], v[2:3], v[134:135]
	global_store_dwordx4 v[138:139], v[0:3], off nt
	global_load_dwordx4 v[0:3], v[6:7], off
	v_add_co_u32_e32 v134, vcc, s19, v16
	v_lshlrev_b32_e32 v136, 16, v110
	s_nop 0
	v_addc_co_u32_e32 v135, vcc, -1, v17, vcc
	v_cmp_gt_f32_e32 vcc, s16, v156
	v_and_b32_e32 v137, 0xffff0000, v110
	v_lshlrev_b32_e32 v138, 16, v111
	v_cndmask_b32_e32 v5, v156, v5, vcc
	v_rsq_f32_e32 v5, v5
	v_and_b32_e32 v139, 0xffff0000, v111
	v_lshlrev_b32_e32 v140, 16, v89
	v_and_b32_e32 v141, 0xffff0000, v89
	v_mul_f32_e32 v110, 0x45800000, v5
	v_cndmask_b32_e32 v110, v5, v110, vcc
	v_pk_mul_f32 v[130:131], v[110:111], v[130:131] op_sel_hi:[0,1]
	v_pk_mul_f32 v[132:133], v[110:111], v[132:133] op_sel_hi:[0,1]
	v_pk_mul_f32 v[128:129], v[110:111], v[128:129] op_sel_hi:[0,1]
	v_pk_mul_f32 v[126:127], v[110:111], v[126:127] op_sel_hi:[0,1]
	v_pk_mul_f32 v[124:125], v[110:111], v[124:125] op_sel_hi:[0,1]
	v_pk_mul_f32 v[122:123], v[110:111], v[122:123] op_sel_hi:[0,1]
	v_pk_mul_f32 v[118:119], v[110:111], v[118:119] op_sel_hi:[0,1]
	v_pk_mul_f32 v[120:121], v[110:111], v[120:121] op_sel_hi:[0,1]
	v_lshlrev_b32_e32 v142, 16, v90
	v_and_b32_e32 v143, 0xffff0000, v90
	v_and_b32_e32 v89, 0xffff0000, v74
	v_lshlrev_b32_e32 v90, 16, v75
	v_and_b32_e32 v75, 0xffff0000, v66
	v_pk_mul_f32 v[56:57], v[110:111], v[56:57] op_sel_hi:[0,1]
	v_pk_mul_f32 v[58:59], v[110:111], v[58:59] op_sel_hi:[0,1]
	v_pk_mul_f32 v[52:53], v[110:111], v[52:53] op_sel_hi:[0,1]
	v_pk_mul_f32 v[54:55], v[110:111], v[54:55] op_sel_hi:[0,1]
	v_mov_b32_e32 v182, v89
	v_mov_b32_e32 v156, v152
	v_mov_b32_e32 v184, v90
	s_waitcnt vmcnt(0)
	v_pk_fma_f32 v[0:1], v[130:131], v[0:1], v[136:137]
	v_pk_fma_f32 v[2:3], v[132:133], v[2:3], v[138:139]
	global_store_dwordx4 v[134:135], v[0:3], off offset:-3072 nt
	global_load_dwordx4 v[0:3], v[6:7], off offset:1024
	v_lshlrev_b32_e32 v130, 16, v116
	v_and_b32_e32 v131, 0xffff0000, v116
	v_lshlrev_b32_e32 v116, 16, v117
	v_and_b32_e32 v117, 0xffff0000, v117
	v_lshlrev_b32_e32 v132, 16, v93
	v_and_b32_e32 v133, 0xffff0000, v93
	v_lshlrev_b32_e32 v136, 16, v88
	v_and_b32_e32 v137, 0xffff0000, v88
	v_lshlrev_b32_e32 v138, 16, v105
	v_and_b32_e32 v139, 0xffff0000, v105
	v_and_b32_e32 v105, 0xffff0000, v81
	v_lshlrev_b32_e32 v88, 16, v74
	v_lshlrev_b32_e32 v74, 16, v66
	v_mov_b32_e32 v171, v105
	v_mov_b32_e32 v180, v88
	v_pk_mul_f32 v[196:197], v[74:75], v[74:75]
	s_waitcnt vmcnt(0)
	v_pk_fma_f32 v[0:1], v[128:129], v[0:1], v[130:131]
	v_pk_fma_f32 v[2:3], v[126:127], v[2:3], v[116:117]
	global_store_dwordx4 v[134:135], v[0:3], off offset:-2048 nt
	global_load_dwordx4 v[0:3], v[6:7], off offset:2048
	v_lshlrev_b32_e32 v116, 16, v112
	v_and_b32_e32 v117, 0xffff0000, v112
	v_lshlrev_b32_e32 v112, 16, v113
	v_and_b32_e32 v113, 0xffff0000, v113
	v_lshlrev_b32_e32 v126, 16, v94
	v_and_b32_e32 v127, 0xffff0000, v94
	v_lshlrev_b32_e32 v128, 16, v95
	v_and_b32_e32 v129, 0xffff0000, v95
	v_lshlrev_b32_e32 v130, 16, v92
	v_and_b32_e32 v131, 0xffff0000, v92
	v_pk_mul_f32 v[92:93], v[110:111], v[106:107] op_sel_hi:[0,1]
	v_pk_mul_f32 v[94:95], v[110:111], v[108:109] op_sel_hi:[0,1]
	v_lshlrev_b32_e32 v108, 16, v83
	v_and_b32_e32 v109, 0xffff0000, v83
	v_lshlrev_b32_e32 v106, 16, v80
	v_and_b32_e32 v107, 0xffff0000, v80
	v_and_b32_e32 v83, 0xffff0000, v70
	v_lshlrev_b32_e32 v80, 16, v71
	v_mov_b32_e32 v170, v107
	v_mov_b32_e32 v190, v83
	v_pk_mul_f32 v[166:167], v[108:109], v[108:109]
	v_mov_b32_e32 v168, v106
	v_mov_b32_e32 v189, v80
	s_waitcnt vmcnt(0)
	v_pk_fma_f32 v[0:1], v[124:125], v[0:1], v[116:117]
	v_pk_fma_f32 v[2:3], v[122:123], v[2:3], v[112:113]
	global_store_dwordx4 v[134:135], v[0:3], off offset:-1024 nt
	global_load_dwordx4 v[0:3], v[6:7], off offset:3072
	v_add_co_u32_e32 v112, vcc, s20, v16
	v_lshlrev_b32_e32 v116, 16, v114
	v_and_b32_e32 v117, 0xffff0000, v114
	v_lshlrev_b32_e32 v114, 16, v115
	v_and_b32_e32 v115, 0xffff0000, v115
	v_addc_co_u32_e32 v113, vcc, -1, v17, vcc
	v_lshlrev_b32_e32 v122, 16, v96
	v_and_b32_e32 v123, 0xffff0000, v96
	v_lshlrev_b32_e32 v124, 16, v97
	v_and_b32_e32 v125, 0xffff0000, v97
	v_lshlrev_b32_e32 v134, 16, v104
	v_and_b32_e32 v135, 0xffff0000, v104
	v_lshlrev_b32_e32 v104, 16, v81
	v_and_b32_e32 v81, 0xffff0000, v71
	v_lshlrev_b32_e32 v96, 16, v79
	v_and_b32_e32 v97, 0xffff0000, v79
	v_and_b32_e32 v79, 0xffff0000, v68
	v_mul_f32_e32 v174, v97, v97
	v_mov_b32_e32 v191, v81
	v_mov_b32_e32 v169, v104
	v_mul_f32_e32 v192, v79, v79
	s_waitcnt vmcnt(0)
; __device__ __forceinline__ float bflo(unsigned v) { return __uint_as_float(v << 16); }
; __device__ __forceinline__ float bfhi(unsigned v) { return __uint_as_float(v & 0xffff0000u); }
; __device__ __forceinline__ void p9_final(const Args& a) {
;     ...
;         for (int r = 0; r < P9R; ++r) { float s2 = 0.f;
; #pragma unroll
;             for (int j = 0; j < 8; ++j) { const float b0 = bflo(fv[r][j].x), b1 = bfhi(fv[r][j].x), b2 = bflo(fv[r][j].y), b3 = bfhi(fv[r][j].y); s2 += (b0 * b0 + b1 * b1) + (b2 * b2 + b3 * b3); }
;             r2[r] = rsqrtf(wave_sum(s2) * (1.0f / DM) + EPS); }
; #pragma unroll
;         for (int r = 0; r < P9R; ++r) { f32x4* orow = (f32x4*)(a.out + (size_t)(m0 + r) * DM) + lane;
; #pragma unroll
;             for (int j = 0; j < 8; ++j) { const f32x4 w2 = wf[64 * j]; f32x4 o;
;                 o[0] = bflo(hv[r][j].x) + bflo(fv[r][j].x) * r2[r] * w2[0]; o[1] = bfhi(hv[r][j].x) + bfhi(fv[r][j].x) * r2[r] * w2[1];
;                 o[2] = bflo(hv[r][j].y) + bflo(fv[r][j].y) * r2[r] * w2[2]; o[3] = bfhi(hv[r][j].y) + bfhi(fv[r][j].y) * r2[r] * w2[3];
;                 orow[64 * j] = o; } }
	v_pk_fma_f32 v[0:1], v[118:119], v[0:1], v[116:117]
	v_pk_fma_f32 v[2:3], v[120:121], v[2:3], v[114:115]
	global_store_dwordx4 v[112:113], v[0:3], off offset:-4096 nt
	global_load_dwordx4 v[0:3], v[8:9], off
	v_lshlrev_b32_e32 v116, 16, v102
	v_and_b32_e32 v117, 0xffff0000, v102
	v_lshlrev_b32_e32 v102, 16, v103
	v_and_b32_e32 v103, 0xffff0000, v103
	v_lshlrev_b32_e32 v118, 16, v84
	v_and_b32_e32 v119, 0xffff0000, v84
	v_lshlrev_b32_e32 v120, 16, v85
	v_and_b32_e32 v121, 0xffff0000, v85
	v_lshlrev_b32_e32 v84, 16, v73
	v_and_b32_e32 v85, 0xffff0000, v73
	v_and_b32_e32 v73, 0xffff0000, v67
	v_pk_mul_f32 v[66:67], v[110:111], v[98:99] op_sel_hi:[0,1]
	v_mul_f32_e32 v160, v119, v119
	v_mov_b32_e32 v187, v85
	v_mul_f32_e32 v162, v121, v121
	v_mov_b32_e32 v185, v84
	v_pk_mul_f32 v[198:199], v[72:73], v[72:73]
	v_add_co_u32_e32 v114, vcc, s3, v16
	s_waitcnt vmcnt(0)
	v_pk_fma_f32 v[0:1], v[92:93], v[0:1], v[116:117]
	v_pk_fma_f32 v[2:3], v[94:95], v[2:3], v[102:103]
	global_store_dwordx4 v[112:113], v[0:3], off offset:-3072 nt
	global_load_dwordx4 v[0:3], v[10:11], off
	v_lshlrev_b32_e32 v116, 16, v82
	v_and_b32_e32 v117, 0xffff0000, v82
	v_lshlrev_b32_e32 v82, 16, v70
	v_pk_mul_f32 v[70:71], v[110:111], v[100:101] op_sel_hi:[0,1]
	v_and_b32_e32 v103, 0xffff0000, v78
	v_lshlrev_b32_e32 v102, 16, v78
	v_lshlrev_b32_e32 v94, 16, v76
	v_and_b32_e32 v95, 0xffff0000, v76
	v_lshlrev_b32_e32 v92, 16, v77
	v_and_b32_e32 v93, 0xffff0000, v77
	v_lshlrev_b32_e32 v78, 16, v68
	v_lshlrev_b32_e32 v76, 16, v69
	v_and_b32_e32 v77, 0xffff0000, v69
	v_lshlrev_b32_e32 v68, 16, v62
	v_and_b32_e32 v69, 0xffff0000, v62
	v_lshlrev_b32_e32 v62, 16, v65
	v_mul_f32_e32 v172, v103, v103
	v_mov_b32_e32 v188, v82
	v_mul_f32_e32 v194, v77, v77
	v_pk_mul_f32 v[164:165], v[116:117], v[116:117]
	v_mov_b32_e32 v202, v69
	v_mov_b32_e32 v200, v68
	v_pk_mul_f32 v[176:177], v[94:95], v[94:95]
	v_pk_mul_f32 v[178:179], v[92:93], v[92:93]
	v_addc_co_u32_e32 v115, vcc, -1, v17, vcc
	s_waitcnt vmcnt(0)
	v_pk_fma_f32 v[0:1], v[66:67], v[0:1], v[122:123]
	v_pk_fma_f32 v[2:3], v[70:71], v[2:3], v[124:125]
	global_store_dwordx4 v[112:113], v[0:3], off offset:-2048 nt
	global_load_dwordx4 v[98:101], v[12:13], off
	v_lshlrev_b32_e32 v70, 16, v63
	v_and_b32_e32 v71, 0xffff0000, v63
	v_lshlrev_b32_e32 v66, 16, v64
	v_and_b32_e32 v67, 0xffff0000, v64
	v_and_b32_e32 v63, 0xffff0000, v65
	v_mov_b32_e32 v64, v135
	v_mov_b32_e32 v65, v143
	v_mov_b32_e32 v124, v139
	v_mov_b32_e32 v125, v145
	v_lshlrev_b32_e32 v0, 16, v60
	v_and_b32_e32 v1, 0xffff0000, v60
	v_lshlrev_b32_e32 v2, 16, v61
	v_and_b32_e32 v3, 0xffff0000, v61
	v_mov_b32_e32 v60, v134
	v_mov_b32_e32 v61, v142
	v_mov_b32_e32 v122, v138
	v_mov_b32_e32 v123, v144
	v_pk_mul_f32 v[64:65], v[64:65], v[64:65]
	v_mul_f32_e32 v204, v67, v67
	v_mul_f32_e32 v206, v63, v63
	v_pk_fma_f32 v[60:61], v[60:61], v[60:61], v[64:65]
	v_mov_b32_e32 v203, v71
	v_mov_b32_e32 v201, v70
	v_pk_mul_f32 v[208:209], v[0:1], v[0:1]
	s_waitcnt vmcnt(0)
	v_pk_fma_f32 v[56:57], v[56:57], v[98:99], v[126:127]
	v_pk_fma_f32 v[58:59], v[58:59], v[100:101], v[128:129]
	global_store_dwordx4 v[112:113], v[56:59], off offset:-1024 nt
	global_load_dwordx4 v[56:59], v[14:15], off
	v_pk_mul_f32 v[100:101], v[124:125], v[124:125]
	v_pk_mul_f32 v[124:125], v[158:159], v[158:159]
	v_pk_fma_f32 v[126:127], v[118:119], v[118:119], v[160:161] op_sel_hi:[1,1,0]
	v_pk_mul_f32 v[158:159], v[170:171], v[170:171]
	v_pk_fma_f32 v[160:161], v[102:103], v[102:103], v[172:173] op_sel_hi:[1,1,0]
	v_pk_mul_f32 v[170:171], v[182:183], v[182:183]
	v_pk_mul_f32 v[172:173], v[186:187], v[186:187]
	v_pk_fma_f32 v[128:129], v[120:121], v[120:121], v[162:163] op_sel_hi:[1,1,0]
	v_pk_fma_f32 v[162:163], v[96:97], v[96:97], v[174:175] op_sel_hi:[1,1,0]
	v_pk_mul_f32 v[174:175], v[190:191], v[190:191]
	v_pk_fma_f32 v[64:65], v[122:123], v[122:123], v[100:101]
	v_pk_fma_f32 v[100:101], v[156:157], v[156:157], v[124:125]
	v_pk_fma_f32 v[124:125], v[180:181], v[180:181], v[170:171]
	v_pk_fma_f32 v[156:157], v[184:185], v[184:185], v[172:173]
	v_pk_mul_f32 v[98:99], v[2:3], v[2:3]
	v_pk_fma_f32 v[182:183], v[78:79], v[78:79], v[192:193] op_sel_hi:[1,1,0]
	v_pk_fma_f32 v[186:187], v[76:77], v[76:77], v[194:195] op_sel_hi:[1,1,0]
	v_pk_fma_f32 v[192:193], v[66:67], v[66:67], v[204:205] op_sel_hi:[1,1,0]
	v_pk_fma_f32 v[194:195], v[62:63], v[62:63], v[206:207] op_sel_hi:[1,1,0]
	v_mov_b32_e32 v127, v166
	v_mov_b32_e32 v129, v167
	v_pk_fma_f32 v[122:123], v[168:169], v[168:169], v[158:159]
	v_pk_fma_f32 v[158:159], v[188:189], v[188:189], v[174:175]
	v_pk_add_f32 v[60:61], v[60:61], v[64:65]
	v_pk_add_f32 v[124:125], v[124:125], v[156:157]
	v_mov_b32_e32 v193, v98
	v_mov_b32_e32 v195, v99
	v_pk_add_f32 v[64:65], v[100:101], v[100:101] op_sel:[0,1] op_sel_hi:[1,0]
	v_pk_add_f32 v[98:99], v[126:127], v[128:129]
	v_pk_add_f32 v[126:127], v[158:159], v[158:159] op_sel:[0,1] op_sel_hi:[1,0]
	v_pk_add_f32 v[60:61], v[60:61], v[60:61] op_sel:[0,1] op_sel_hi:[1,0]
	v_pk_add_f32 v[124:125], v[124:125], v[124:125] op_sel:[0,1] op_sel_hi:[1,0]
	v_mov_b32_e32 v183, v198
	v_mov_b32_e32 v187, v199
	v_mov_b32_e32 v65, v165
	v_mov_b32_e32 v127, v197
	v_mov_b32_e32 v61, v164
	v_mov_b32_e32 v125, v196
	v_pk_mul_f32 v[190:191], v[202:203], v[202:203]
	v_pk_add_f32 v[128:129], v[182:183], v[186:187]
	v_pk_add_f32 v[60:61], v[60:61], v[64:65]
	v_pk_add_f32 v[64:65], v[124:125], v[126:127]
	v_pk_fma_f32 v[166:167], v[200:201], v[200:201], v[190:191]
	v_pk_add_f32 v[60:61], v[60:61], v[98:99]
	v_pk_add_f32 v[64:65], v[64:65], v[128:129]
	v_pk_add_f32 v[100:101], v[122:123], v[122:123] op_sel:[0,1] op_sel_hi:[1,0]
	v_pk_add_f32 v[156:157], v[166:167], v[166:167] op_sel:[0,1] op_sel_hi:[1,0]
	v_pk_add_f32 v[60:61], v[60:61], v[60:61] op_sel:[0,1] op_sel_hi:[1,0]
	v_pk_add_f32 v[64:65], v[64:65], v[64:65] op_sel:[0,1] op_sel_hi:[1,0]
	v_mov_b32_e32 v161, v178
	v_mov_b32_e32 v163, v179
	v_mov_b32_e32 v101, v177
	v_mov_b32_e32 v157, v209
	v_mov_b32_e32 v61, v176
	v_mov_b32_e32 v65, v208
	v_pk_add_f32 v[122:123], v[160:161], v[162:163]
	v_pk_add_f32 v[158:159], v[192:193], v[194:195]
	s_waitcnt vmcnt(0)
; __device__ __forceinline__ float bflo(unsigned v) { return __uint_as_float(v << 16); }
; __device__ __forceinline__ float bfhi(unsigned v) { return __uint_as_float(v & 0xffff0000u); }
; __device__ __forceinline__ void p9_final(const Args& a) {
;     ...
;         for (int r = 0; r < P9R; ++r) { float s2 = 0.f;
; #pragma unroll
;             for (int j = 0; j < 8; ++j) { const float b0 = bflo(fv[r][j].x), b1 = bfhi(fv[r][j].x), b2 = bflo(fv[r][j].y), b3 = bfhi(fv[r][j].y); s2 += (b0 * b0 + b1 * b1) + (b2 * b2 + b3 * b3); }
;             r2[r] = rsqrtf(wave_sum(s2) * (1.0f / DM) + EPS); }
; #pragma unroll
;         for (int r = 0; r < P9R; ++r) { f32x4* orow = (f32x4*)(a.out + (size_t)(m0 + r) * DM) + lane;
; #pragma unroll
;             for (int j = 0; j < 8; ++j) { const f32x4 w2 = wf[64 * j]; f32x4 o;
;                 o[0] = bflo(hv[r][j].x) + bflo(fv[r][j].x) * r2[r] * w2[0]; o[1] = bfhi(hv[r][j].x) + bfhi(fv[r][j].x) * r2[r] * w2[1];
;                 o[2] = bflo(hv[r][j].y) + bflo(fv[r][j].y) * r2[r] * w2[2]; o[3] = bfhi(hv[r][j].y) + bfhi(fv[r][j].y) * r2[r] * w2[3];
;                 orow[64 * j] = o; } }
	v_pk_fma_f32 v[52:53], v[52:53], v[56:57], v[130:131]
	v_pk_fma_f32 v[54:55], v[54:55], v[58:59], v[132:133]
	global_store_dwordx4 v[112:113], v[52:55], off nt
	global_load_dwordx4 v[52:55], v[6:7], off
	v_pk_add_f32 v[56:57], v[60:61], v[100:101]
	v_pk_add_f32 v[58:59], v[64:65], v[156:157]
	v_pk_add_f32 v[56:57], v[56:57], v[122:123]
	v_pk_add_f32 v[58:59], v[58:59], v[158:159]
	v_mov_b32_e32 v61, v56
	v_mov_b32_e32 v60, v58
	v_mov_b32_e32 v56, v59
	v_pk_add_f32 v[56:57], v[60:61], v[56:57]
	ds_bpermute_b32 v59, v146, v57
	ds_bpermute_b32 v58, v146, v56
	s_waitcnt lgkmcnt(0)
	v_pk_add_f32 v[56:57], v[56:57], v[58:59]
	ds_bpermute_b32 v59, v147, v57
	ds_bpermute_b32 v58, v147, v56
	s_waitcnt lgkmcnt(0)
	v_pk_add_f32 v[56:57], v[56:57], v[58:59]
	ds_bpermute_b32 v59, v148, v57
	ds_bpermute_b32 v58, v148, v56
	s_waitcnt lgkmcnt(0)
	v_pk_add_f32 v[56:57], v[56:57], v[58:59]
	ds_bpermute_b32 v59, v149, v57
	ds_bpermute_b32 v58, v149, v56
	s_waitcnt lgkmcnt(0)
	v_pk_add_f32 v[56:57], v[56:57], v[58:59]
	ds_bpermute_b32 v59, v150, v57
	ds_bpermute_b32 v58, v150, v56
	s_waitcnt lgkmcnt(0)
	v_pk_add_f32 v[56:57], v[56:57], v[58:59]
	ds_bpermute_b32 v59, v151, v57
	ds_bpermute_b32 v58, v151, v56
	s_waitcnt lgkmcnt(0)
	v_pk_add_f32 v[56:57], v[56:57], v[58:59]
	s_nop 0
	v_pk_fma_f32 v[56:57], v[56:57], s[10:11], v[20:21] op_sel_hi:[1,0,0]
	s_nop 0
	v_mul_f32_e32 v5, 0x4b800000, v57
	v_cmp_gt_f32_e32 vcc, s16, v57
	s_nop 1
	v_cndmask_b32_e32 v5, v57, v5, vcc
	v_rsq_f32_e32 v5, v5
	s_nop 0
	v_mul_f32_e32 v57, 0x45800000, v5
	v_cndmask_b32_e32 v58, v5, v57, vcc
	v_pk_mul_f32 v[60:61], v[58:59], v[134:135] op_sel_hi:[0,1]
	v_pk_mul_f32 v[64:65], v[58:59], v[138:139] op_sel_hi:[0,1]
	v_pk_mul_f32 v[98:99], v[58:59], v[144:145] op_sel_hi:[0,1]
	v_mul_f32_e32 v5, 0x4b800000, v56
	s_waitcnt vmcnt(0)
	v_pk_fma_f32 v[52:53], v[60:61], v[52:53], v[136:137]
	v_pk_fma_f32 v[54:55], v[64:65], v[54:55], v[140:141]
	global_store_dwordx4 v[114:115], v[52:55], off offset:-3072 nt
	global_load_dwordx4 v[52:55], v[6:7], off offset:1024
	v_lshlrev_b32_e32 v60, 16, v50
	v_and_b32_e32 v61, 0xffff0000, v50
	v_lshlrev_b32_e32 v64, 16, v51
	v_and_b32_e32 v65, 0xffff0000, v51
	v_pk_mul_f32 v[50:51], v[58:59], v[142:143] op_sel_hi:[0,1]
	s_waitcnt vmcnt(0)
	v_pk_fma_f32 v[50:51], v[50:51], v[52:53], v[60:61]
	v_pk_fma_f32 v[52:53], v[98:99], v[54:55], v[64:65]
	global_store_dwordx4 v[114:115], v[50:53], off offset:-2048 nt
	global_load_dwordx4 v[50:53], v[6:7], off offset:2048
	v_lshlrev_b32_e32 v54, 16, v48
	v_and_b32_e32 v55, 0xffff0000, v48
	v_lshlrev_b32_e32 v60, 16, v49
	v_and_b32_e32 v61, 0xffff0000, v49
	v_pk_mul_f32 v[48:49], v[58:59], v[152:153] op_sel_hi:[0,1]
	v_pk_mul_f32 v[64:65], v[58:59], v[154:155] op_sel_hi:[0,1]
	s_waitcnt vmcnt(0)
	v_pk_fma_f32 v[48:49], v[48:49], v[50:51], v[54:55]
	v_pk_fma_f32 v[50:51], v[64:65], v[52:53], v[60:61]
	global_store_dwordx4 v[114:115], v[48:51], off offset:-1024 nt
	global_load_dwordx4 v[48:51], v[6:7], off offset:3072
	v_add_co_u32_e32 v52, vcc, s11, v16
	v_lshlrev_b32_e32 v54, 16, v46
	v_and_b32_e32 v55, 0xffff0000, v46
	v_lshlrev_b32_e32 v60, 16, v47
	v_and_b32_e32 v61, 0xffff0000, v47
	v_pk_mul_f32 v[46:47], v[58:59], v[118:119] op_sel_hi:[0,1]
	v_pk_mul_f32 v[64:65], v[58:59], v[120:121] op_sel_hi:[0,1]
	v_addc_co_u32_e32 v53, vcc, -1, v17, vcc
	s_waitcnt vmcnt(0)
	v_pk_fma_f32 v[46:47], v[46:47], v[48:49], v[54:55]
	v_pk_fma_f32 v[48:49], v[64:65], v[50:51], v[60:61]
	global_store_dwordx4 v[52:53], v[46:49], off offset:-4096 nt
	global_load_dwordx4 v[46:49], v[8:9], off
	v_lshlrev_b32_e32 v50, 16, v44
	v_and_b32_e32 v51, 0xffff0000, v44
	v_lshlrev_b32_e32 v54, 16, v45
	v_and_b32_e32 v55, 0xffff0000, v45
	v_pk_mul_f32 v[44:45], v[58:59], v[116:117] op_sel_hi:[0,1]
	v_pk_mul_f32 v[60:61], v[58:59], v[108:109] op_sel_hi:[0,1]
	s_waitcnt vmcnt(0)
	v_pk_fma_f32 v[44:45], v[44:45], v[46:47], v[50:51]
	v_pk_fma_f32 v[46:47], v[60:61], v[48:49], v[54:55]
	global_store_dwordx4 v[52:53], v[44:47], off offset:-3072 nt
	global_load_dwordx4 v[44:47], v[10:11], off
	v_lshlrev_b32_e32 v48, 16, v42
	v_and_b32_e32 v49, 0xffff0000, v42
	v_lshlrev_b32_e32 v50, 16, v43
	v_and_b32_e32 v51, 0xffff0000, v43
	v_pk_mul_f32 v[42:43], v[58:59], v[106:107] op_sel_hi:[0,1]
	v_pk_mul_f32 v[54:55], v[58:59], v[104:105] op_sel_hi:[0,1]
	s_waitcnt vmcnt(0)
	v_pk_fma_f32 v[42:43], v[42:43], v[44:45], v[48:49]
	v_pk_fma_f32 v[44:45], v[54:55], v[46:47], v[50:51]
	global_store_dwordx4 v[52:53], v[42:45], off offset:-2048 nt
	global_load_dwordx4 v[42:45], v[12:13], off
	v_lshlrev_b32_e32 v46, 16, v40
	v_and_b32_e32 v47, 0xffff0000, v40
	v_lshlrev_b32_e32 v48, 16, v41
	v_and_b32_e32 v49, 0xffff0000, v41
	v_pk_mul_f32 v[40:41], v[58:59], v[102:103] op_sel_hi:[0,1]
	v_pk_mul_f32 v[50:51], v[58:59], v[96:97] op_sel_hi:[0,1]
	s_waitcnt vmcnt(0)
; __device__ __forceinline__ float bflo(unsigned v) { return __uint_as_float(v << 16); }
; __device__ __forceinline__ float bfhi(unsigned v) { return __uint_as_float(v & 0xffff0000u); }
; __device__ __forceinline__ void p9_final(const Args& a) {
;     ...
;     for (int m0 = gw * P9R; m0 < M; m0 += NGW * P9R) {
;         u32x2 hv[P9R][8], fv[P9R][8];
; #pragma unroll
;         for (int r = 0; r < P9R; ++r) { const u32x2* hp = (const u32x2*)(H1 + (size_t)(m0 + r) * DM) + lane; const u32x2* fp = (const u32x2*)(FFN + (size_t)(m0 + r) * DM) + lane;
; #pragma unroll
;             for (int j = 0; j < 8; ++j) { hv[r][j] = hp[64 * j]; fv[r][j] = fp[64 * j]; } }
;         float r2[P9R];
; #pragma unroll
;         for (int r = 0; r < P9R; ++r) { float s2 = 0.f;
; #pragma unroll
;             for (int j = 0; j < 8; ++j) { const float b0 = bflo(fv[r][j].x), b1 = bfhi(fv[r][j].x), b2 = bflo(fv[r][j].y), b3 = bfhi(fv[r][j].y); s2 += (b0 * b0 + b1 * b1) + (b2 * b2 + b3 * b3); }
;             r2[r] = rsqrtf(wave_sum(s2) * (1.0f / DM) + EPS); }
; #pragma unroll
;         for (int r = 0; r < P9R; ++r) { f32x4* orow = (f32x4*)(a.out + (size_t)(m0 + r) * DM) + lane;
; #pragma unroll
;             for (int j = 0; j < 8; ++j) { const f32x4 w2 = wf[64 * j]; f32x4 o;
;                 o[0] = bflo(hv[r][j].x) + bflo(fv[r][j].x) * r2[r] * w2[0]; o[1] = bfhi(hv[r][j].x) + bfhi(fv[r][j].x) * r2[r] * w2[1];
;                 o[2] = bflo(hv[r][j].y) + bflo(fv[r][j].y) * r2[r] * w2[2]; o[3] = bfhi(hv[r][j].y) + bfhi(fv[r][j].y) * r2[r] * w2[3];
;                 orow[64 * j] = o; } }
	v_pk_fma_f32 v[40:41], v[40:41], v[42:43], v[46:47]
	v_pk_fma_f32 v[42:43], v[50:51], v[44:45], v[48:49]
	global_store_dwordx4 v[52:53], v[40:43], off offset:-1024 nt
	global_load_dwordx4 v[40:43], v[14:15], off
	v_lshlrev_b32_e32 v44, 16, v38
	v_and_b32_e32 v45, 0xffff0000, v38
	v_lshlrev_b32_e32 v46, 16, v39
	v_and_b32_e32 v47, 0xffff0000, v39
	v_pk_mul_f32 v[38:39], v[58:59], v[94:95] op_sel_hi:[0,1]
	v_pk_mul_f32 v[48:49], v[58:59], v[92:93] op_sel_hi:[0,1]
	s_waitcnt vmcnt(0)
	v_pk_fma_f32 v[38:39], v[38:39], v[40:41], v[44:45]
	v_pk_fma_f32 v[40:41], v[48:49], v[42:43], v[46:47]
	global_store_dwordx4 v[52:53], v[38:41], off nt
	global_load_dwordx4 v[38:41], v[6:7], off
	v_add_co_u32_e32 v42, vcc, s13, v16
	v_lshlrev_b32_e32 v44, 16, v36
	s_nop 0
	v_addc_co_u32_e32 v43, vcc, -1, v17, vcc
	v_cmp_gt_f32_e32 vcc, s16, v56
	v_and_b32_e32 v45, 0xffff0000, v36
	v_lshlrev_b32_e32 v46, 16, v37
	v_cndmask_b32_e32 v5, v56, v5, vcc
	v_rsq_f32_e32 v5, v5
	v_and_b32_e32 v47, 0xffff0000, v37
	v_mul_f32_e32 v36, 0x45800000, v5
	v_cndmask_b32_e32 v48, v5, v36, vcc
	v_pk_mul_f32 v[36:37], v[48:49], v[88:89] op_sel_hi:[0,1]
	v_pk_mul_f32 v[50:51], v[48:49], v[90:91] op_sel_hi:[0,1]
	v_pk_mul_f32 v[0:1], v[48:49], v[0:1] op_sel_hi:[0,1]
	v_pk_mul_f32 v[2:3], v[48:49], v[2:3] op_sel_hi:[0,1]
	v_cmp_lt_i32_e32 vcc, s21, v4
	s_or_b64 s[8:9], vcc, s[8:9]
	s_waitcnt vmcnt(0)
	v_pk_fma_f32 v[36:37], v[36:37], v[38:39], v[44:45]
	v_pk_fma_f32 v[38:39], v[50:51], v[40:41], v[46:47]
	global_store_dwordx4 v[42:43], v[36:39], off offset:-3072 nt
	global_load_dwordx4 v[36:39], v[6:7], off offset:1024
	v_lshlrev_b32_e32 v40, 16, v34
	v_and_b32_e32 v41, 0xffff0000, v34
	v_lshlrev_b32_e32 v44, 16, v35
	v_and_b32_e32 v45, 0xffff0000, v35
	v_pk_mul_f32 v[34:35], v[48:49], v[86:87] op_sel_hi:[0,1]
	v_pk_mul_f32 v[46:47], v[48:49], v[84:85] op_sel_hi:[0,1]
	s_waitcnt vmcnt(0)
	v_pk_fma_f32 v[34:35], v[34:35], v[36:37], v[40:41]
	v_pk_fma_f32 v[36:37], v[46:47], v[38:39], v[44:45]
	global_store_dwordx4 v[42:43], v[34:37], off offset:-2048 nt
	global_load_dwordx4 v[34:37], v[6:7], off offset:2048
	v_lshlrev_b32_e32 v38, 16, v32
	v_and_b32_e32 v39, 0xffff0000, v32
	v_lshlrev_b32_e32 v40, 16, v33
	v_and_b32_e32 v41, 0xffff0000, v33
	v_pk_mul_f32 v[32:33], v[48:49], v[82:83] op_sel_hi:[0,1]
	v_pk_mul_f32 v[44:45], v[48:49], v[80:81] op_sel_hi:[0,1]
	s_waitcnt vmcnt(0)
	v_pk_fma_f32 v[32:33], v[32:33], v[34:35], v[38:39]
	v_pk_fma_f32 v[34:35], v[44:45], v[36:37], v[40:41]
	global_store_dwordx4 v[42:43], v[32:35], off offset:-1024 nt
	global_load_dwordx4 v[32:35], v[6:7], off offset:3072
	v_lshlrev_b32_e32 v36, 16, v30
	v_and_b32_e32 v37, 0xffff0000, v30
	v_lshlrev_b32_e32 v38, 16, v31
	v_and_b32_e32 v39, 0xffff0000, v31
	v_pk_mul_f32 v[30:31], v[48:49], v[78:79] op_sel_hi:[0,1]
	v_pk_mul_f32 v[40:41], v[48:49], v[76:77] op_sel_hi:[0,1]
	s_waitcnt vmcnt(0)
	v_pk_fma_f32 v[30:31], v[30:31], v[32:33], v[36:37]
	v_pk_fma_f32 v[32:33], v[40:41], v[34:35], v[38:39]
	global_store_dwordx4 v[16:17], v[30:33], off offset:-4096 nt
	global_load_dwordx4 v[30:33], v[8:9], off
	v_lshlrev_b32_e32 v34, 16, v28
	v_and_b32_e32 v35, 0xffff0000, v28
	v_lshlrev_b32_e32 v36, 16, v29
	v_and_b32_e32 v37, 0xffff0000, v29
	v_pk_mul_f32 v[28:29], v[48:49], v[74:75] op_sel_hi:[0,1]
	v_pk_mul_f32 v[38:39], v[48:49], v[72:73] op_sel_hi:[0,1]
	s_waitcnt vmcnt(0)
	v_pk_fma_f32 v[28:29], v[28:29], v[30:31], v[34:35]
	v_pk_fma_f32 v[30:31], v[38:39], v[32:33], v[36:37]
	global_store_dwordx4 v[16:17], v[28:31], off offset:-3072 nt
	global_load_dwordx4 v[28:31], v[10:11], off
	v_lshlrev_b32_e32 v32, 16, v26
	v_and_b32_e32 v33, 0xffff0000, v26
	v_lshlrev_b32_e32 v34, 16, v27
	v_and_b32_e32 v35, 0xffff0000, v27
	v_pk_mul_f32 v[26:27], v[48:49], v[68:69] op_sel_hi:[0,1]
	v_pk_mul_f32 v[36:37], v[48:49], v[70:71] op_sel_hi:[0,1]
	s_waitcnt vmcnt(0)
	v_pk_fma_f32 v[26:27], v[26:27], v[28:29], v[32:33]
	v_pk_fma_f32 v[28:29], v[36:37], v[30:31], v[34:35]
	global_store_dwordx4 v[16:17], v[26:29], off offset:-2048 nt
	global_load_dwordx4 v[26:29], v[12:13], off
	v_lshlrev_b32_e32 v30, 16, v24
	v_and_b32_e32 v31, 0xffff0000, v24
	v_lshlrev_b32_e32 v32, 16, v25
	v_and_b32_e32 v33, 0xffff0000, v25
	v_pk_mul_f32 v[24:25], v[48:49], v[66:67] op_sel_hi:[0,1]
	v_pk_mul_f32 v[34:35], v[48:49], v[62:63] op_sel_hi:[0,1]
	s_waitcnt vmcnt(0)
	v_pk_fma_f32 v[24:25], v[24:25], v[26:27], v[30:31]
	v_pk_fma_f32 v[26:27], v[34:35], v[28:29], v[32:33]
	global_store_dwordx4 v[16:17], v[24:27], off offset:-1024 nt
	global_load_dwordx4 v[24:27], v[14:15], off
	v_lshlrev_b32_e32 v28, 16, v22
	v_and_b32_e32 v29, 0xffff0000, v22
	v_lshlrev_b32_e32 v22, 16, v23
	v_and_b32_e32 v23, 0xffff0000, v23
	s_waitcnt vmcnt(0)
	v_pk_fma_f32 v[0:1], v[0:1], v[24:25], v[28:29]
	v_pk_fma_f32 v[2:3], v[2:3], v[26:27], v[22:23]
	global_store_dwordx4 v[16:17], v[0:3], off nt
	v_lshl_add_u64 v[16:17], v[16:17], 0, s[4:5]
	s_andn2_b64 exec, exec, s[8:9]
	s_cbranch_execnz .LBB0_1380
